# attention part A: exps reordered so the MFMA-result wait states are covered by work (two s_nop pads dropped), three K fragment reads issued earlier
# baseline (speedup 1.0000x reference)
; #define SB() __builtin_amdgcn_sched_barrier(0)
; #define EXPACK(sc_, rbq_, p0_, p1_) do { float ps_ = 0.f; \
;                 _Pragma("unroll") for (int r = 0; r < 16; ++r) { sc_[r] = __builtin_amdgcn_exp2f(SHIFT ? sc_[r] - bound2 : sc_[r]); ps_ += sc_[r]; } \
;                 lsum[rbq_] += ps_; p0_ = pack8(sc_, 0); p1_ = pack8(sc_, 1); } while (0)
; #define BLOAD(B_, ks_) do { asm volatile("" : "+v"(v0l)); _Pragma("unroll") for (int cb = 0; cb < 4; ++cb) B_[cb] = BFRAG(ks_, cb); SB(); } while (0)
; #define PVMMA(B_, pA_, pB_) do { _Pragma("unroll") for (int cb = 0; cb < 4; ++cb) { o[0][cb] = MFMA32(pA_, B_[cb], o[0][cb]); o[1][cb] = MFMA32(pB_, B_[cb], o[1][cb]); } } while (0)
; template <bool SHIFT> DI void phase_attn2(const Params& p, const Grp& G, int layer, LAS unsigned char* lds, int tid, int wave, int lane, int vcu, bool dry) {
;     ...
;             {
;                 f32x16 s0, s1; bf16x8 pa00, pa01, pa10, pa11; bf16x8 kfs[4], qfs[4];
;                 CHAIN(s0, 0, 0, true, true); CHAIN(s1, 0, 1, false, true);
;                 EXPACK(s0, 0, pa00, pa01); EXPACK(s1, 1, pa10, pa11);
;                 SB();
;                 CHAIN(s1, 1, 1, true, false); CHAIN(s0, 1, 0, false, true);
;                 bf16x8 pb00, pb01, pb10, pb11; bf16x8 B[4];
;                 BLOAD(B, 0);
;                 PVMMA(B, pa00, pa10); EXPACK(s0, 0, pb00, pb01);
.LBB0_378:
	ds_read_b128 v[128:131], v217
	ds_read_b128 v[160:163], v236
	ds_read_b128 v[166:169], v237
	ds_read_b128 v[170:173], v238
	ds_read_b128 v[132:135], v222
	ds_read_b128 v[136:139], v222 offset:1024
	ds_read_b128 v[140:143], v222 offset:2048
	ds_read_b128 v[174:177], v222 offset:3072
	s_waitcnt lgkmcnt(0)
	v_mfma_f32_32x32x16_bf16 v[144:159], v[128:131], v[132:135], 0
	v_mfma_f32_32x32x16_bf16 v[144:159], v[160:163], v[136:139], v[144:159]
	v_mfma_f32_32x32x16_bf16 v[144:159], v[166:169], v[140:143], v[144:159]
	v_mfma_f32_32x32x16_bf16 v[144:159], v[170:173], v[174:177], v[144:159]
	ds_read_b128 v[174:177], v222 offset:4096
	ds_read_b128 v[178:181], v222 offset:5120
	ds_read_b128 v[182:185], v222 offset:6144
	ds_read_b128 v[224:227], v222 offset:7168
	s_waitcnt lgkmcnt(0)
	v_mfma_f32_32x32x16_bf16 v[128:143], v[128:131], v[174:177], 0
	v_mfma_f32_32x32x16_bf16 v[128:143], v[160:163], v[178:181], v[128:143]
	v_mfma_f32_32x32x16_bf16 v[128:143], v[166:169], v[182:185], v[128:143]
	v_mfma_f32_32x32x16_bf16 v[128:143], v[170:173], v[224:227], v[128:143]
	ds_read_b128 v[170:173], v236 offset:8192
	ds_read_b128 v[228:231], v237 offset:8192
	ds_read_b128 v[232:235], v238 offset:8192
	v_exp_f32_e32 v144, v144
	v_exp_f32_e32 v145, v145
	v_exp_f32_e32 v146, v146
	v_exp_f32_e32 v147, v147
	v_exp_f32_e32 v148, v148
	v_exp_f32_e32 v149, v149
	v_exp_f32_e32 v150, v150
	v_exp_f32_e32 v188, v151
	v_exp_f32_e32 v208, v152
	v_exp_f32_e32 v206, v153
	v_exp_f32_e32 v204, v154
	v_exp_f32_e32 v202, v155
	v_exp_f32_e32 v200, v156
	v_exp_f32_e32 v198, v157
	v_exp_f32_e32 v196, v158
	v_exp_f32_e32 v190, v159
	v_exp_f32_e32 v189, v135
	v_add_f32_e32 v135, v145, v144
	v_exp_f32_e32 v128, v128
	v_exp_f32_e32 v129, v129
	v_exp_f32_e32 v130, v130
	v_exp_f32_e32 v131, v131
	v_exp_f32_e32 v132, v132
	v_exp_f32_e32 v133, v133
	v_exp_f32_e32 v134, v134
	v_add_f32_e32 v135, v146, v135
	v_add_f32_e32 v135, v147, v135
	v_add_f32_e32 v135, v148, v135
	v_add_f32_e32 v135, v149, v135
	v_cvt_pk_bf16_f32 v160, v144, v145
	v_cvt_pk_bf16_f32 v161, v146, v147
	v_cvt_pk_bf16_f32 v162, v148, v149
	v_cvt_pk_bf16_f32 v163, v150, v188
	v_exp_f32_e32 v209, v136
	v_exp_f32_e32 v207, v137
	v_exp_f32_e32 v205, v138
	v_exp_f32_e32 v203, v139
	v_exp_f32_e32 v201, v140
	v_exp_f32_e32 v199, v141
	v_exp_f32_e32 v197, v142
	v_exp_f32_e32 v191, v143
	v_add_f32_e32 v210, v150, v135
	v_cvt_pk_bf16_f32 v166, v128, v129
	v_cvt_pk_bf16_f32 v167, v130, v131
	v_cvt_pk_bf16_f32 v168, v132, v133
	v_cvt_pk_bf16_f32 v169, v134, v189
	ds_read_b128 v[144:147], v217 offset:8192
	v_add_f32_e32 v128, v129, v128
	v_add_f32_e32 v128, v130, v128
	v_add_f32_e32 v128, v131, v128
	v_add_f32_e32 v128, v132, v128
	v_add_f32_e32 v128, v133, v128
	v_add_f32_e32 v211, v134, v128
	s_waitcnt lgkmcnt(0)
	v_mfma_f32_32x32x16_bf16 v[128:143], v[144:147], v[174:177], 0
	v_mfma_f32_32x32x16_bf16 v[128:143], v[170:173], v[178:181], v[128:143]
	v_mfma_f32_32x32x16_bf16 v[128:143], v[228:231], v[182:185], v[128:143]
	v_mfma_f32_32x32x16_bf16 v[128:143], v[232:235], v[224:227], v[128:143]
	ds_read_b128 v[148:151], v222
	ds_read_b128 v[174:177], v222 offset:1024
	ds_read_b128 v[178:181], v222 offset:2048
	ds_read_b128 v[182:185], v222 offset:3072
	s_waitcnt lgkmcnt(0)
	v_mfma_f32_32x32x16_bf16 v[144:159], v[144:147], v[148:151], 0
	v_mfma_f32_32x32x16_bf16 v[144:159], v[170:173], v[174:177], v[144:159]
	v_mfma_f32_32x32x16_bf16 v[144:159], v[228:231], v[178:181], v[144:159]
	v_mfma_f32_32x32x16_bf16 v[144:159], v[232:235], v[182:185], v[144:159]
	s_nop 4
	ds_read_b64_tr_b16 v[170:171], v218 offset:16384
	ds_read_b64_tr_b16 v[172:173], v239 offset:18432
	ds_read_b64_tr_b16 v[174:175], v240 offset:16384
	ds_read_b64_tr_b16 v[176:177], v241 offset:18432
	ds_read_b64_tr_b16 v[178:179], v248 offset:16384
	ds_read_b64_tr_b16 v[180:181], v249 offset:18432
	ds_read_b64_tr_b16 v[182:183], v250 offset:16384
	ds_read_b64_tr_b16 v[184:185], v251 offset:18432
	v_exp_f32_e32 v144, v144
	s_waitcnt lgkmcnt(6)
	v_mfma_f32_32x32x16_bf16 v[112:127], v[160:163], v[170:173], v[112:127]
	v_exp_f32_e32 v145, v145
	v_exp_f32_e32 v146, v146
	v_exp_f32_e32 v147, v147
	v_exp_f32_e32 v148, v148
	v_exp_f32_e32 v149, v149
	v_mfma_f32_32x32x16_bf16 v[0:15], v[166:169], v[170:173], v[0:15]
	v_exp_f32_e32 v170, v151
	v_exp_f32_e32 v172, v154
	s_waitcnt lgkmcnt(4)
	v_mfma_f32_32x32x16_bf16 v[96:111], v[160:163], v[174:177], v[96:111]
	v_mfma_f32_32x32x16_bf16 v[16:31], v[166:169], v[174:177], v[16:31]
	v_exp_f32_e32 v174, v153
	v_exp_f32_e32 v176, v156
	s_waitcnt lgkmcnt(2)
	v_mfma_f32_32x32x16_bf16 v[80:95], v[160:163], v[178:181], v[80:95]
	v_mfma_f32_32x32x16_bf16 v[32:47], v[166:169], v[178:181], v[32:47]
	v_exp_f32_e32 v178, v155
	v_exp_f32_e32 v180, v158
	s_waitcnt lgkmcnt(0)
; #define SB() __builtin_amdgcn_sched_barrier(0)
; #define EXPACK(sc_, rbq_, p0_, p1_) do { float ps_ = 0.f; \
;                 _Pragma("unroll") for (int r = 0; r < 16; ++r) { sc_[r] = __builtin_amdgcn_exp2f(SHIFT ? sc_[r] - bound2 : sc_[r]); ps_ += sc_[r]; } \
;                 lsum[rbq_] += ps_; p0_ = pack8(sc_, 0); p1_ = pack8(sc_, 1); } while (0)
; #define BLOAD(B_, ks_) do { asm volatile("" : "+v"(v0l)); _Pragma("unroll") for (int cb = 0; cb < 4; ++cb) B_[cb] = BFRAG(ks_, cb); SB(); } while (0)
; #define PVMMA(B_, pA_, pB_) do { _Pragma("unroll") for (int cb = 0; cb < 4; ++cb) { o[0][cb] = MFMA32(pA_, B_[cb], o[0][cb]); o[1][cb] = MFMA32(pB_, B_[cb], o[1][cb]); } } while (0)
; template <bool SHIFT> DI void phase_attn2(const Params& p, const Grp& G, int layer, LAS unsigned char* lds, int tid, int wave, int lane, int vcu, bool dry) {
;     ...
;                 PVMMA(B, pa00, pa10); EXPACK(s0, 0, pb00, pb01);
;                 SB();
;                 BLOAD(B, 1);
;                 PVMMA(B, pa01, pa11); EXPACK(s1, 1, pb10, pb11);
;                 SB();
;                 BLOAD(B, 2);
;                 PVMMA(B, pb00, pb10);
;                 SB();
;                 BLOAD(B, 3);
;                 PVMMA(B, pb01, pb11);
;                 SB();
;             }
	v_mfma_f32_32x32x16_bf16 v[64:79], v[160:163], v[182:185], v[64:79]
	v_add_f32_e32 v160, v145, v144
	v_add_f32_e32 v160, v146, v160
	v_add_f32_e32 v160, v147, v160
	v_add_f32_e32 v160, v148, v160
	v_add_f32_e32 v186, v149, v160
	v_cvt_pk_bf16_f32 v144, v144, v145
	v_mfma_f32_32x32x16_bf16 v[48:63], v[166:169], v[182:185], v[48:63]
	v_exp_f32_e32 v166, v150
	v_exp_f32_e32 v168, v152
	v_exp_f32_e32 v182, v157
	v_exp_f32_e32 v184, v159
	v_cvt_pk_bf16_f32 v145, v146, v147
	v_cvt_pk_bf16_f32 v146, v148, v149
	s_nop 0
	ds_read_b64_tr_b16 v[160:161], v218 offset:20480
	ds_read_b64_tr_b16 v[162:163], v239 offset:22528
	ds_read_b64_tr_b16 v[156:157], v240 offset:20480
	ds_read_b64_tr_b16 v[158:159], v241 offset:22528
	ds_read_b64_tr_b16 v[152:153], v248 offset:20480
	ds_read_b64_tr_b16 v[154:155], v249 offset:22528
	ds_read_b64_tr_b16 v[148:149], v250 offset:20480
	ds_read_b64_tr_b16 v[150:151], v251 offset:22528
	v_exp_f32_e32 v223, v128
	v_exp_f32_e32 v224, v129
	v_exp_f32_e32 v225, v130
	v_exp_f32_e32 v226, v131
	v_exp_f32_e32 v227, v132
	v_add_f32_e32 v128, v224, v223
	v_exp_f32_e32 v228, v133
	v_exp_f32_e32 v167, v134
	v_exp_f32_e32 v171, v135
	v_cvt_pk_bf16_f32 v132, v208, v206
	v_cvt_pk_bf16_f32 v133, v204, v202
	v_cvt_pk_bf16_f32 v134, v200, v198
	v_cvt_pk_bf16_f32 v135, v196, v190
	v_add_f32_e32 v128, v225, v128
	v_exp_f32_e32 v169, v136
	v_exp_f32_e32 v175, v137
	v_exp_f32_e32 v173, v138
	v_exp_f32_e32 v179, v139
	v_cvt_pk_bf16_f32 v136, v209, v207
	v_cvt_pk_bf16_f32 v137, v205, v203
	v_cvt_pk_bf16_f32 v138, v201, v199
	v_cvt_pk_bf16_f32 v139, v197, v191
	v_add_f32_e32 v128, v226, v128
	v_add_f32_e32 v128, v227, v128
	v_add_f32_e32 v187, v228, v128
	v_pk_add_f32 v[128:129], v[188:189], v[210:211]
	s_waitcnt lgkmcnt(6)
	v_mfma_f32_32x32x16_bf16 v[112:127], v[132:135], v[160:163], v[112:127]
	v_add_f32_e64 v128, v208, v128
	v_add_f32_e64 v129, v209, v129
	v_exp_f32_e32 v177, v140
	v_pk_add_f32 v[128:129], v[206:207], v[128:129]
	v_exp_f32_e32 v183, v141
	v_pk_add_f32 v[128:129], v[204:205], v[128:129]
	v_exp_f32_e32 v181, v142
	v_pk_add_f32 v[128:129], v[202:203], v[128:129]
	s_waitcnt lgkmcnt(4)
	v_mfma_f32_32x32x16_bf16 v[96:111], v[132:135], v[156:159], v[96:111]
	v_exp_f32_e32 v185, v143
	v_pk_add_f32 v[128:129], v[200:201], v[128:129]
	v_cvt_pk_bf16_f32 v147, v166, v170
	v_pk_add_f32 v[128:129], v[198:199], v[128:129]
	v_cvt_pk_bf16_f32 v130, v176, v182
	v_pk_add_f32 v[128:129], v[196:197], v[128:129]
	v_cvt_pk_bf16_f32 v131, v180, v184
	s_waitcnt lgkmcnt(2)
	v_mfma_f32_32x32x16_bf16 v[80:95], v[132:135], v[152:155], v[80:95]
	v_add_f32_e64 v128, v190, v128
	v_add_f32_e64 v129, v191, v129
	v_add_f32_e64 v140, v164, v128
	v_add_f32_e64 v141, v165, v129
	v_cvt_pk_bf16_f32 v128, v168, v174
	v_cvt_pk_bf16_f32 v129, v172, v178
	s_waitcnt lgkmcnt(0)
	v_mfma_f32_32x32x16_bf16 v[64:79], v[132:135], v[148:151], v[64:79]
	v_add_f32_e64 v132, v166, v186
	v_add_f32_e64 v133, v167, v187
	v_cvt_pk_bf16_f32 v134, v227, v228
	v_add_f32_e64 v132, v170, v132
	v_add_f32_e64 v133, v171, v133
	v_cvt_pk_bf16_f32 v135, v167, v171
	v_pk_add_f32 v[132:133], v[168:169], v[132:133]
	s_nop 0
	v_pk_add_f32 v[132:133], v[174:175], v[132:133]
	v_mfma_f32_32x32x16_bf16 v[0:15], v[136:139], v[160:163], v[0:15]
	v_add_f32_e64 v132, v172, v132
	v_add_f32_e64 v133, v173, v133
	v_add_f32_e64 v132, v178, v132
	v_add_f32_e64 v133, v179, v133
	v_add_f32_e64 v132, v176, v132
	v_add_f32_e64 v133, v177, v133
	v_pk_add_f32 v[132:133], v[182:183], v[132:133]
	v_mfma_f32_32x32x16_bf16 v[16:31], v[136:139], v[156:159], v[16:31]
	v_add_f32_e64 v132, v180, v132
	v_add_f32_e64 v133, v181, v133
	v_add_f32_e64 v142, v184, v132
	v_add_f32_e64 v143, v185, v133
	v_cvt_pk_bf16_f32 v132, v223, v224
	v_cvt_pk_bf16_f32 v133, v225, v226
	v_mfma_f32_32x32x16_bf16 v[32:47], v[136:139], v[152:155], v[32:47]
	v_mfma_f32_32x32x16_bf16 v[48:63], v[136:139], v[148:151], v[48:63]
	v_cvt_pk_bf16_f32 v136, v169, v175
	v_cvt_pk_bf16_f32 v137, v173, v179
	v_cvt_pk_bf16_f32 v138, v177, v183
	v_cvt_pk_bf16_f32 v139, v181, v185
	s_nop 0
	ds_read_b64_tr_b16 v[148:149], v218 offset:24576
	ds_read_b64_tr_b16 v[150:151], v239 offset:26624
	ds_read_b64_tr_b16 v[152:153], v240 offset:24576
	ds_read_b64_tr_b16 v[154:155], v241 offset:26624
	ds_read_b64_tr_b16 v[156:157], v248 offset:24576
	ds_read_b64_tr_b16 v[158:159], v249 offset:26624
	ds_read_b64_tr_b16 v[160:161], v250 offset:24576
	ds_read_b64_tr_b16 v[162:163], v251 offset:26624
	s_waitcnt lgkmcnt(6)
	v_mfma_f32_32x32x16_bf16 v[112:127], v[144:147], v[148:151], v[112:127]
	v_add_f32_e64 v164, v140, v142
	v_add_f32_e64 v165, v141, v143
	v_mfma_f32_32x32x16_bf16 v[0:15], v[132:135], v[148:151], v[0:15]
	s_waitcnt lgkmcnt(4)
	v_mfma_f32_32x32x16_bf16 v[96:111], v[144:147], v[152:155], v[96:111]
	v_mfma_f32_32x32x16_bf16 v[16:31], v[132:135], v[152:155], v[16:31]
	s_waitcnt lgkmcnt(2)
	v_mfma_f32_32x32x16_bf16 v[80:95], v[144:147], v[156:159], v[80:95]
	v_mfma_f32_32x32x16_bf16 v[32:47], v[132:135], v[156:159], v[32:47]
	s_waitcnt lgkmcnt(0)
	v_mfma_f32_32x32x16_bf16 v[64:79], v[144:147], v[160:163], v[64:79]
	v_mfma_f32_32x32x16_bf16 v[48:63], v[132:135], v[160:163], v[48:63]
	s_nop 0
	ds_read_b64_tr_b16 v[132:133], v218 offset:28672
	ds_read_b64_tr_b16 v[134:135], v239 offset:30720
	ds_read_b64_tr_b16 v[140:141], v240 offset:28672
	ds_read_b64_tr_b16 v[142:143], v241 offset:30720
	ds_read_b64_tr_b16 v[144:145], v248 offset:28672
	ds_read_b64_tr_b16 v[146:147], v249 offset:30720
	ds_read_b64_tr_b16 v[148:149], v250 offset:28672
	ds_read_b64_tr_b16 v[150:151], v251 offset:30720
	s_waitcnt lgkmcnt(6)
	v_mfma_f32_32x32x16_bf16 v[112:127], v[128:131], v[132:135], v[112:127]
	v_mfma_f32_32x32x16_bf16 v[0:15], v[136:139], v[132:135], v[0:15]
	s_waitcnt lgkmcnt(4)
	v_mfma_f32_32x32x16_bf16 v[96:111], v[128:131], v[140:143], v[96:111]
	v_mfma_f32_32x32x16_bf16 v[16:31], v[136:139], v[140:143], v[16:31]
	s_waitcnt lgkmcnt(2)
	v_mfma_f32_32x32x16_bf16 v[80:95], v[128:131], v[144:147], v[80:95]
	v_mfma_f32_32x32x16_bf16 v[32:47], v[136:139], v[144:147], v[32:47]
	s_waitcnt lgkmcnt(0)
	v_mfma_f32_32x32x16_bf16 v[64:79], v[128:131], v[148:151], v[64:79]
	v_mfma_f32_32x32x16_bf16 v[48:63], v[136:139], v[148:151], v[48:63]
	s_waitcnt vmcnt(0)
	s_add_u32 s30, s30, 0x50000
	s_addc_u32 s31, s31, 0
	s_cmp_eq_u32 s45, s38
	s_mov_b32 s8, s39
	s_barrier
	s_cbranch_scc1 .LBB0_383
	s_branch .Lat2_top_O

; #define SB() __builtin_amdgcn_sched_barrier(0)
; #define EXPACK(sc_, rbq_, p0_, p1_) do { float ps_ = 0.f; \
;                 _Pragma("unroll") for (int r = 0; r < 16; ++r) { sc_[r] = __builtin_amdgcn_exp2f(SHIFT ? sc_[r] - bound2 : sc_[r]); ps_ += sc_[r]; } \
;                 lsum[rbq_] += ps_; p0_ = pack8(sc_, 0); p1_ = pack8(sc_, 1); } while (0)
; #define BLOAD(B_, ks_) do { asm volatile("" : "+v"(v0l)); _Pragma("unroll") for (int cb = 0; cb < 4; ++cb) B_[cb] = BFRAG(ks_, cb); SB(); } while (0)
; #define PVMMA(B_, pA_, pB_) do { _Pragma("unroll") for (int cb = 0; cb < 4; ++cb) { o[0][cb] = MFMA32(pA_, B_[cb], o[0][cb]); o[1][cb] = MFMA32(pB_, B_[cb], o[1][cb]); } } while (0)
; template <bool SHIFT> DI void phase_attn2(const Params& p, const Grp& G, int layer, LAS unsigned char* lds, int tid, int wave, int lane, int vcu, bool dry) {
;     ...
;             {
;                 f32x16 s0, s1; bf16x8 pa00, pa01, pa10, pa11; bf16x8 kfs[4], qfs[4];
;                 CHAIN(s0, 0, 0, true, true); CHAIN(s1, 0, 1, false, true);
;                 EXPACK(s0, 0, pa00, pa01); EXPACK(s1, 1, pa10, pa11);
;                 SB();
;                 CHAIN(s1, 1, 1, true, false); CHAIN(s0, 1, 0, false, true);
;                 bf16x8 pb00, pb01, pb10, pb11; bf16x8 B[4];
;                 BLOAD(B, 0);
;                 PVMMA(B, pa00, pa10); EXPACK(s0, 0, pb00, pb01);
.Lat2_body_O:
	ds_read_b128 v[128:131], v217 offset:32768
	ds_read_b128 v[160:163], v236 offset:32768
	ds_read_b128 v[166:169], v237 offset:32768
	ds_read_b128 v[170:173], v238 offset:32768
	ds_read_b128 v[132:135], v222
	ds_read_b128 v[136:139], v222 offset:1024
	ds_read_b128 v[140:143], v222 offset:2048
	ds_read_b128 v[174:177], v222 offset:3072
	s_waitcnt lgkmcnt(0)
	v_mfma_f32_32x32x16_bf16 v[144:159], v[128:131], v[132:135], 0
	v_mfma_f32_32x32x16_bf16 v[144:159], v[160:163], v[136:139], v[144:159]
	v_mfma_f32_32x32x16_bf16 v[144:159], v[166:169], v[140:143], v[144:159]
	v_mfma_f32_32x32x16_bf16 v[144:159], v[170:173], v[174:177], v[144:159]
	ds_read_b128 v[174:177], v222 offset:4096
	ds_read_b128 v[178:181], v222 offset:5120
	ds_read_b128 v[182:185], v222 offset:6144
	ds_read_b128 v[224:227], v222 offset:7168
	s_waitcnt lgkmcnt(0)
	v_mfma_f32_32x32x16_bf16 v[128:143], v[128:131], v[174:177], 0
	v_mfma_f32_32x32x16_bf16 v[128:143], v[160:163], v[178:181], v[128:143]
	v_mfma_f32_32x32x16_bf16 v[128:143], v[166:169], v[182:185], v[128:143]
	v_mfma_f32_32x32x16_bf16 v[128:143], v[170:173], v[224:227], v[128:143]
	ds_read_b128 v[170:173], v236 offset:40960
	ds_read_b128 v[228:231], v237 offset:40960
	ds_read_b128 v[232:235], v238 offset:40960
	v_exp_f32_e32 v144, v144
	v_exp_f32_e32 v145, v145
	v_exp_f32_e32 v146, v146
	v_exp_f32_e32 v147, v147
	v_exp_f32_e32 v148, v148
	v_exp_f32_e32 v149, v149
	v_exp_f32_e32 v150, v150
	v_exp_f32_e32 v188, v151
	v_exp_f32_e32 v208, v152
	v_exp_f32_e32 v206, v153
	v_exp_f32_e32 v204, v154
	v_exp_f32_e32 v202, v155
	v_exp_f32_e32 v200, v156
	v_exp_f32_e32 v198, v157
	v_exp_f32_e32 v196, v158
	v_exp_f32_e32 v190, v159
	v_exp_f32_e32 v189, v135
	v_add_f32_e32 v135, v145, v144
	v_exp_f32_e32 v128, v128
	v_exp_f32_e32 v129, v129
	v_exp_f32_e32 v130, v130
	v_exp_f32_e32 v131, v131
	v_exp_f32_e32 v132, v132
	v_exp_f32_e32 v133, v133
	v_exp_f32_e32 v134, v134
	v_add_f32_e32 v135, v146, v135
	v_add_f32_e32 v135, v147, v135
	v_add_f32_e32 v135, v148, v135
	v_add_f32_e32 v135, v149, v135
	v_cvt_pk_bf16_f32 v160, v144, v145
	v_cvt_pk_bf16_f32 v161, v146, v147
	v_cvt_pk_bf16_f32 v162, v148, v149
	v_cvt_pk_bf16_f32 v163, v150, v188
	v_exp_f32_e32 v209, v136
	v_exp_f32_e32 v207, v137
	v_exp_f32_e32 v205, v138
	v_exp_f32_e32 v203, v139
	v_exp_f32_e32 v201, v140
	v_exp_f32_e32 v199, v141
	v_exp_f32_e32 v197, v142
	v_exp_f32_e32 v191, v143
	v_add_f32_e32 v210, v150, v135
	v_cvt_pk_bf16_f32 v166, v128, v129
	v_cvt_pk_bf16_f32 v167, v130, v131
	v_cvt_pk_bf16_f32 v168, v132, v133
	v_cvt_pk_bf16_f32 v169, v134, v189
	ds_read_b128 v[144:147], v217 offset:40960
	v_add_f32_e32 v128, v129, v128
	v_add_f32_e32 v128, v130, v128
	v_add_f32_e32 v128, v131, v128
	v_add_f32_e32 v128, v132, v128
	v_add_f32_e32 v128, v133, v128
	v_add_f32_e32 v211, v134, v128
	s_waitcnt lgkmcnt(0)
	v_mfma_f32_32x32x16_bf16 v[128:143], v[144:147], v[174:177], 0
	v_mfma_f32_32x32x16_bf16 v[128:143], v[170:173], v[178:181], v[128:143]
	v_mfma_f32_32x32x16_bf16 v[128:143], v[228:231], v[182:185], v[128:143]
	v_mfma_f32_32x32x16_bf16 v[128:143], v[232:235], v[224:227], v[128:143]
	ds_read_b128 v[148:151], v222
	ds_read_b128 v[174:177], v222 offset:1024
	ds_read_b128 v[178:181], v222 offset:2048
	ds_read_b128 v[182:185], v222 offset:3072
	s_waitcnt lgkmcnt(0)
	v_mfma_f32_32x32x16_bf16 v[144:159], v[144:147], v[148:151], 0
	v_mfma_f32_32x32x16_bf16 v[144:159], v[170:173], v[174:177], v[144:159]
	v_mfma_f32_32x32x16_bf16 v[144:159], v[228:231], v[178:181], v[144:159]
	v_mfma_f32_32x32x16_bf16 v[144:159], v[232:235], v[182:185], v[144:159]
	s_nop 4
	ds_read_b64_tr_b16 v[170:171], v218 offset:49152
	ds_read_b64_tr_b16 v[172:173], v239 offset:51200
	ds_read_b64_tr_b16 v[174:175], v240 offset:49152
	ds_read_b64_tr_b16 v[176:177], v241 offset:51200
	ds_read_b64_tr_b16 v[178:179], v248 offset:49152
	ds_read_b64_tr_b16 v[180:181], v249 offset:51200
	ds_read_b64_tr_b16 v[182:183], v250 offset:49152
	ds_read_b64_tr_b16 v[184:185], v251 offset:51200
	v_exp_f32_e32 v144, v144
	s_waitcnt lgkmcnt(6)
	v_mfma_f32_32x32x16_bf16 v[112:127], v[160:163], v[170:173], v[112:127]
	v_exp_f32_e32 v145, v145
	v_exp_f32_e32 v146, v146
	v_exp_f32_e32 v147, v147
	v_exp_f32_e32 v148, v148
	v_exp_f32_e32 v149, v149
	v_mfma_f32_32x32x16_bf16 v[0:15], v[166:169], v[170:173], v[0:15]
	v_exp_f32_e32 v170, v151
	v_exp_f32_e32 v172, v154
	s_waitcnt lgkmcnt(4)
	v_mfma_f32_32x32x16_bf16 v[96:111], v[160:163], v[174:177], v[96:111]
	v_mfma_f32_32x32x16_bf16 v[16:31], v[166:169], v[174:177], v[16:31]
	v_exp_f32_e32 v174, v153
	v_exp_f32_e32 v176, v156
	s_waitcnt lgkmcnt(2)
	v_mfma_f32_32x32x16_bf16 v[80:95], v[160:163], v[178:181], v[80:95]
	v_mfma_f32_32x32x16_bf16 v[32:47], v[166:169], v[178:181], v[32:47]
	v_exp_f32_e32 v178, v155
	v_exp_f32_e32 v180, v158
	s_waitcnt lgkmcnt(0)
; #define SB() __builtin_amdgcn_sched_barrier(0)
; #define EXPACK(sc_, rbq_, p0_, p1_) do { float ps_ = 0.f; \
;                 _Pragma("unroll") for (int r = 0; r < 16; ++r) { sc_[r] = __builtin_amdgcn_exp2f(SHIFT ? sc_[r] - bound2 : sc_[r]); ps_ += sc_[r]; } \
;                 lsum[rbq_] += ps_; p0_ = pack8(sc_, 0); p1_ = pack8(sc_, 1); } while (0)
; #define BLOAD(B_, ks_) do { asm volatile("" : "+v"(v0l)); _Pragma("unroll") for (int cb = 0; cb < 4; ++cb) B_[cb] = BFRAG(ks_, cb); SB(); } while (0)
; #define PVMMA(B_, pA_, pB_) do { _Pragma("unroll") for (int cb = 0; cb < 4; ++cb) { o[0][cb] = MFMA32(pA_, B_[cb], o[0][cb]); o[1][cb] = MFMA32(pB_, B_[cb], o[1][cb]); } } while (0)
; template <bool SHIFT> DI void phase_attn2(const Params& p, const Grp& G, int layer, LAS unsigned char* lds, int tid, int wave, int lane, int vcu, bool dry) {
;     ...
;                 PVMMA(B, pa00, pa10); EXPACK(s0, 0, pb00, pb01);
;                 SB();
;                 BLOAD(B, 1);
;                 PVMMA(B, pa01, pa11); EXPACK(s1, 1, pb10, pb11);
;                 SB();
;                 BLOAD(B, 2);
;                 PVMMA(B, pb00, pb10);
;                 SB();
;                 BLOAD(B, 3);
;                 PVMMA(B, pb01, pb11);
;                 SB();
;             }
;     ...
;             asm volatile("s_waitcnt vmcnt(0)" ::: "memory");
;             __syncthreads();
	v_mfma_f32_32x32x16_bf16 v[64:79], v[160:163], v[182:185], v[64:79]
	v_add_f32_e32 v160, v145, v144
	v_add_f32_e32 v160, v146, v160
	v_add_f32_e32 v160, v147, v160
	v_add_f32_e32 v160, v148, v160
	v_add_f32_e32 v186, v149, v160
	v_cvt_pk_bf16_f32 v144, v144, v145
	v_mfma_f32_32x32x16_bf16 v[48:63], v[166:169], v[182:185], v[48:63]
	v_exp_f32_e32 v166, v150
	v_exp_f32_e32 v168, v152
	v_exp_f32_e32 v182, v157
	v_exp_f32_e32 v184, v159
	v_cvt_pk_bf16_f32 v145, v146, v147
	v_cvt_pk_bf16_f32 v146, v148, v149
	s_nop 0
	ds_read_b64_tr_b16 v[160:161], v218 offset:53248
	ds_read_b64_tr_b16 v[162:163], v239 offset:55296
	ds_read_b64_tr_b16 v[156:157], v240 offset:53248
	ds_read_b64_tr_b16 v[158:159], v241 offset:55296
	ds_read_b64_tr_b16 v[152:153], v248 offset:53248
	ds_read_b64_tr_b16 v[154:155], v249 offset:55296
	ds_read_b64_tr_b16 v[148:149], v250 offset:53248
	ds_read_b64_tr_b16 v[150:151], v251 offset:55296
	v_exp_f32_e32 v223, v128
	v_exp_f32_e32 v224, v129
	v_exp_f32_e32 v225, v130
	v_exp_f32_e32 v226, v131
	v_exp_f32_e32 v227, v132
	v_add_f32_e32 v128, v224, v223
	v_exp_f32_e32 v228, v133
	v_exp_f32_e32 v167, v134
	v_exp_f32_e32 v171, v135
	v_cvt_pk_bf16_f32 v132, v208, v206
	v_cvt_pk_bf16_f32 v133, v204, v202
	v_cvt_pk_bf16_f32 v134, v200, v198
	v_cvt_pk_bf16_f32 v135, v196, v190
	v_add_f32_e32 v128, v225, v128
	v_exp_f32_e32 v169, v136
	v_exp_f32_e32 v175, v137
	v_exp_f32_e32 v173, v138
	v_exp_f32_e32 v179, v139
	v_cvt_pk_bf16_f32 v136, v209, v207
	v_cvt_pk_bf16_f32 v137, v205, v203
	v_cvt_pk_bf16_f32 v138, v201, v199
	v_cvt_pk_bf16_f32 v139, v197, v191
	v_add_f32_e32 v128, v226, v128
	v_add_f32_e32 v128, v227, v128
	v_add_f32_e32 v187, v228, v128
	v_pk_add_f32 v[128:129], v[188:189], v[210:211]
	s_waitcnt lgkmcnt(6)
	v_mfma_f32_32x32x16_bf16 v[112:127], v[132:135], v[160:163], v[112:127]
	v_add_f32_e64 v128, v208, v128
	v_add_f32_e64 v129, v209, v129
	v_exp_f32_e32 v177, v140
	v_pk_add_f32 v[128:129], v[206:207], v[128:129]
	v_exp_f32_e32 v183, v141
	v_pk_add_f32 v[128:129], v[204:205], v[128:129]
	v_exp_f32_e32 v181, v142
	v_pk_add_f32 v[128:129], v[202:203], v[128:129]
	s_waitcnt lgkmcnt(4)
	v_mfma_f32_32x32x16_bf16 v[96:111], v[132:135], v[156:159], v[96:111]
	v_exp_f32_e32 v185, v143
	v_pk_add_f32 v[128:129], v[200:201], v[128:129]
	v_cvt_pk_bf16_f32 v147, v166, v170
	v_pk_add_f32 v[128:129], v[198:199], v[128:129]
	v_cvt_pk_bf16_f32 v130, v176, v182
	v_pk_add_f32 v[128:129], v[196:197], v[128:129]
	v_cvt_pk_bf16_f32 v131, v180, v184
	s_waitcnt lgkmcnt(2)
	v_mfma_f32_32x32x16_bf16 v[80:95], v[132:135], v[152:155], v[80:95]
	v_add_f32_e64 v128, v190, v128
	v_add_f32_e64 v129, v191, v129
	v_add_f32_e64 v140, v164, v128
	v_add_f32_e64 v141, v165, v129
	v_cvt_pk_bf16_f32 v128, v168, v174
	v_cvt_pk_bf16_f32 v129, v172, v178
	s_waitcnt lgkmcnt(0)
	v_mfma_f32_32x32x16_bf16 v[64:79], v[132:135], v[148:151], v[64:79]
	v_add_f32_e64 v132, v166, v186
	v_add_f32_e64 v133, v167, v187
	v_cvt_pk_bf16_f32 v134, v227, v228
	v_add_f32_e64 v132, v170, v132
	v_add_f32_e64 v133, v171, v133
	v_cvt_pk_bf16_f32 v135, v167, v171
	v_pk_add_f32 v[132:133], v[168:169], v[132:133]
	s_nop 0
	v_pk_add_f32 v[132:133], v[174:175], v[132:133]
	v_mfma_f32_32x32x16_bf16 v[0:15], v[136:139], v[160:163], v[0:15]
	v_add_f32_e64 v132, v172, v132
	v_add_f32_e64 v133, v173, v133
	v_add_f32_e64 v132, v178, v132
	v_add_f32_e64 v133, v179, v133
	v_add_f32_e64 v132, v176, v132
	v_add_f32_e64 v133, v177, v133
	v_pk_add_f32 v[132:133], v[182:183], v[132:133]
	v_mfma_f32_32x32x16_bf16 v[16:31], v[136:139], v[156:159], v[16:31]
	v_add_f32_e64 v132, v180, v132
	v_add_f32_e64 v133, v181, v133
	v_add_f32_e64 v142, v184, v132
	v_add_f32_e64 v143, v185, v133
	v_cvt_pk_bf16_f32 v132, v223, v224
	v_cvt_pk_bf16_f32 v133, v225, v226
	v_mfma_f32_32x32x16_bf16 v[32:47], v[136:139], v[152:155], v[32:47]
	v_mfma_f32_32x32x16_bf16 v[48:63], v[136:139], v[148:151], v[48:63]
	v_cvt_pk_bf16_f32 v136, v169, v175
	v_cvt_pk_bf16_f32 v137, v173, v179
	v_cvt_pk_bf16_f32 v138, v177, v183
	v_cvt_pk_bf16_f32 v139, v181, v185
	s_nop 0
	ds_read_b64_tr_b16 v[148:149], v218 offset:57344
	ds_read_b64_tr_b16 v[150:151], v239 offset:59392
	ds_read_b64_tr_b16 v[152:153], v240 offset:57344
	ds_read_b64_tr_b16 v[154:155], v241 offset:59392
	ds_read_b64_tr_b16 v[156:157], v248 offset:57344
	ds_read_b64_tr_b16 v[158:159], v249 offset:59392
	ds_read_b64_tr_b16 v[160:161], v250 offset:57344
	ds_read_b64_tr_b16 v[162:163], v251 offset:59392
	s_waitcnt lgkmcnt(6)
	v_mfma_f32_32x32x16_bf16 v[112:127], v[144:147], v[148:151], v[112:127]
	v_add_f32_e64 v164, v140, v142
	v_add_f32_e64 v165, v141, v143
	v_mfma_f32_32x32x16_bf16 v[0:15], v[132:135], v[148:151], v[0:15]
	s_waitcnt lgkmcnt(4)
	v_mfma_f32_32x32x16_bf16 v[96:111], v[144:147], v[152:155], v[96:111]
	v_mfma_f32_32x32x16_bf16 v[16:31], v[132:135], v[152:155], v[16:31]
	s_waitcnt lgkmcnt(2)
	v_mfma_f32_32x32x16_bf16 v[80:95], v[144:147], v[156:159], v[80:95]
	v_mfma_f32_32x32x16_bf16 v[32:47], v[132:135], v[156:159], v[32:47]
	s_waitcnt lgkmcnt(0)
	v_mfma_f32_32x32x16_bf16 v[64:79], v[144:147], v[160:163], v[64:79]
	v_mfma_f32_32x32x16_bf16 v[48:63], v[132:135], v[160:163], v[48:63]
	s_nop 0
	ds_read_b64_tr_b16 v[132:133], v218 offset:61440
	ds_read_b64_tr_b16 v[134:135], v239 offset:63488
	ds_read_b64_tr_b16 v[140:141], v240 offset:61440
	ds_read_b64_tr_b16 v[142:143], v241 offset:63488
	ds_read_b64_tr_b16 v[144:145], v248 offset:61440
	ds_read_b64_tr_b16 v[146:147], v249 offset:63488
	ds_read_b64_tr_b16 v[148:149], v250 offset:61440
	ds_read_b64_tr_b16 v[150:151], v251 offset:63488
	s_waitcnt lgkmcnt(6)
	v_mfma_f32_32x32x16_bf16 v[112:127], v[128:131], v[132:135], v[112:127]
	v_mfma_f32_32x32x16_bf16 v[0:15], v[136:139], v[132:135], v[0:15]
	s_waitcnt lgkmcnt(4)
	v_mfma_f32_32x32x16_bf16 v[96:111], v[128:131], v[140:143], v[96:111]
	v_mfma_f32_32x32x16_bf16 v[16:31], v[136:139], v[140:143], v[16:31]
	s_waitcnt lgkmcnt(2)
	v_mfma_f32_32x32x16_bf16 v[80:95], v[128:131], v[144:147], v[80:95]
	v_mfma_f32_32x32x16_bf16 v[32:47], v[136:139], v[144:147], v[32:47]
	s_waitcnt lgkmcnt(0)
	v_mfma_f32_32x32x16_bf16 v[64:79], v[128:131], v[148:151], v[64:79]
	v_mfma_f32_32x32x16_bf16 v[48:63], v[136:139], v[148:151], v[48:63]
	s_waitcnt vmcnt(0)
	s_add_u32 s30, s30, 0x50000
	s_addc_u32 s31, s31, 0
	s_cmp_eq_u32 s45, s38
	s_mov_b32 s8, s39
	s_barrier
	s_cbranch_scc1 .LBB0_383
	s_branch .LBB0_379
